# v78 + P3 scan normaliser: its sixteen loads issued behind the batch-2 copies (sl == 0 workgroups no longer trail the scan by a load latency)
# speedup vs baseline: 1.0120x; 1.0043x over previous
.LBB0_956:
	s_or_b64 exec, exec, s[4:5]
	v_ashrrev_i32_e32 v1, 4, v84
	v_lshl_add_u32 v232, s6, 5, v1
	v_lshlrev_b32_e32 v233, 4, v84
	s_ashr_i32 s1, s0, 31
	v_and_b32_e32 v85, 0xf0, v233
	s_lshl_b64 s[4:5], s[0:1], 12
	v_ashrrev_i32_e32 v233, 31, v232
	v_lshl_add_u64 v[234:235], s[4:5], 0, v[232:233]
	v_lshlrev_b64 v[234:235], 9, v[234:235]
	v_ashrrev_i32_e32 v232, 1, v232
	s_lshl_b64 s[8:9], s[0:1], 21
	v_bfi_b32 v232, -16, v232, v84
	v_lshl_add_u64 v[234:235], s[96:97], 0, v[234:235]
	v_lshlrev_b32_e32 v82, 1, v85
	v_mov_b32_e32 v83, 0
	s_add_u32 s8, s96, s8
	v_ashrrev_i32_e32 v233, 31, v232
	v_lshl_add_u64 v[88:89], v[234:235], 0, v[82:83]
	s_mov_b32 s7, 0x23b80000
	s_addc_u32 s9, s97, s9
	v_lshlrev_b64 v[232:233], 10, v[232:233]
	v_add_co_u32_e32 v234, vcc, s7, v88
	v_lshl_add_u64 v[232:233], s[8:9], 0, v[232:233]
	s_nop 0
	v_addc_co_u32_e32 v235, vcc, 0, v89, vcc
	s_mov_b64 s[8:9], 0x23b80000
	v_lshl_add_u64 v[234:235], v[88:89], 0, s[8:9]
	s_mov_b32 s7, 0x23ba0000
	v_add_co_u32_e32 v234, vcc, s7, v88
	v_and_b32_e32 v82, 0x1f0, v84
	s_mov_b64 s[8:9], 0x23ba0000
	v_addc_co_u32_e32 v235, vcc, 0, v89, vcc
	v_lshl_add_u64 v[86:87], v[232:233], 0, v[82:83]
	v_lshl_add_u64 v[232:233], v[88:89], 0, s[8:9]
	s_mov_b32 s7, 0x23bc0000
	v_add_co_u32_e32 v234, vcc, s7, v88
	s_mov_b64 s[8:9], 0x23bc0000
	s_nop 0
	v_addc_co_u32_e32 v235, vcc, 0, v89, vcc
	v_lshl_add_u64 v[232:233], v[88:89], 0, s[8:9]
	s_mov_b32 s7, 0x23be0000
	v_add_co_u32_e32 v234, vcc, s7, v88
	s_mov_b64 s[8:9], 0x23be0000
	s_nop 0
	v_addc_co_u32_e32 v235, vcc, 0, v89, vcc
	v_lshl_add_u64 v[232:233], v[88:89], 0, s[8:9]
	s_mov_b32 s7, 0x23c00000
	v_add_co_u32_e32 v234, vcc, s7, v88
	s_mov_b64 s[8:9], 0x23c00000
	s_nop 0
	v_addc_co_u32_e32 v235, vcc, 0, v89, vcc
	v_lshl_add_u64 v[232:233], v[88:89], 0, s[8:9]
	s_mov_b32 s7, 0x23c20000
	v_add_co_u32_e32 v234, vcc, s7, v88
	s_mov_b64 s[8:9], 0x23c20000
	s_nop 0
	v_addc_co_u32_e32 v235, vcc, 0, v89, vcc
	v_lshl_add_u64 v[232:233], v[88:89], 0, s[8:9]
	s_mov_b32 s7, 0x23c40000
	v_add_co_u32_e32 v234, vcc, s7, v88
	s_mov_b64 s[8:9], 0x23c40000
	s_nop 0
	v_addc_co_u32_e32 v235, vcc, 0, v89, vcc
	v_lshl_add_u64 v[232:233], v[88:89], 0, s[8:9]
	s_mov_b32 s7, 0x23c60000
	v_add_co_u32_e32 v240, vcc, s7, v88
	s_mov_b64 s[8:9], 0x23c60000
	s_nop 0
	v_addc_co_u32_e32 v241, vcc, 0, v89, vcc
	v_lshl_add_u64 v[242:243], v[88:89], 0, s[8:9]
	ds_read_b128 v[54:57], v83
	ds_read_b128 v[58:61], v83 offset:64
	ds_read_b128 v[66:69], v83 offset:16
	s_mov_b32 s7, 0x27ba0000
	v_add_co_u32_e32 v102, vcc, s7, v86
	s_waitcnt lgkmcnt(2)
	v_mul_f32_e32 v82, 0, v54
	v_addc_co_u32_e32 v103, vcc, 0, v87, vcc
	s_mov_b32 s7, 0x27bc0000
	ds_read_b128 v[70:73], v83 offset:80
	s_mov_b64 s[8:9], 0x23c80000
	v_lshlrev_b32_e32 v1, 2, v1
	v_readlane_b32 s36, v245, 25
	v_readlane_b32 s50, v245, 39
	v_readlane_b32 s51, v245, 40
	s_movk_i32 s10, 0x84
	v_readlane_b32 s37, v245, 26
	v_readlane_b32 s38, v245, 27
	v_readlane_b32 s39, v245, 28
	s_waitcnt vmcnt(60)
	v_lshlrev_b32_e32 v90, 16, v78
	v_and_b32_e32 v91, 0xffff0000, v78
	s_waitcnt vmcnt(59)
	v_lshlrev_b32_e32 v94, 16, v74
	v_and_b32_e32 v95, 0xffff0000, v74
	v_lshlrev_b32_e32 v74, 16, v75
	v_and_b32_e32 v75, 0xffff0000, v75
	v_lshlrev_b32_e32 v78, 16, v79
	v_and_b32_e32 v79, 0xffff0000, v79
	v_lshlrev_b32_e32 v92, 16, v80
	v_and_b32_e32 v93, 0xffff0000, v80
	v_lshlrev_b32_e32 v80, 16, v81
	v_and_b32_e32 v81, 0xffff0000, v81
	s_waitcnt lgkmcnt(2)
	v_pk_fma_f32 v[96:97], v[58:59], v[74:75], v[82:83] op_sel_hi:[0,1,0]
	v_lshlrev_b32_e32 v74, 16, v76
	v_and_b32_e32 v75, 0xffff0000, v76
	v_pk_fma_f32 v[90:91], v[58:59], v[90:91], v[82:83] op_sel_hi:[0,1,0]
	v_pk_fma_f32 v[78:79], v[58:59], v[78:79], v[82:83] op_sel_hi:[0,1,0]
	v_pk_fma_f32 v[92:93], v[58:59], v[92:93], v[82:83] op_sel_hi:[0,1,0]
	v_pk_fma_f32 v[80:81], v[58:59], v[80:81], v[82:83] op_sel_hi:[0,1,0]
	v_pk_fma_f32 v[98:99], v[58:59], v[74:75], v[82:83] op_sel_hi:[0,1,0]
	v_lshlrev_b32_e32 v74, 16, v77
	v_and_b32_e32 v75, 0xffff0000, v77
	v_pk_fma_f32 v[94:95], v[58:59], v[94:95], v[82:83] op_sel_hi:[0,1,0]
	v_pk_fma_f32 v[100:101], v[58:59], v[74:75], v[82:83] op_sel_hi:[0,1,0]
	v_cvt_pk_bf16_f32 v74, v90, v91
	v_cvt_pk_bf16_f32 v75, v78, v79
	v_cvt_pk_bf16_f32 v76, v92, v93
	v_cvt_pk_bf16_f32 v77, v80, v81
	global_store_dwordx4 v[102:103], v[74:77], off
	v_readlane_b32 s40, v245, 29
	v_readlane_b32 s41, v245, 30
	v_cvt_pk_bf16_f32 v74, v94, v95
	v_cvt_pk_bf16_f32 v75, v96, v97
	v_cvt_pk_bf16_f32 v76, v98, v99
	v_cvt_pk_bf16_f32 v77, v100, v101
	global_store_dwordx4 v[102:103], v[74:77], off offset:512
	v_readlane_b32 s42, v245, 31
	v_readlane_b32 s43, v245, 32
	s_waitcnt vmcnt(60)
	v_lshlrev_b32_e32 v74, 16, v62
	v_and_b32_e32 v75, 0xffff0000, v62
	v_lshlrev_b32_e32 v62, 16, v63
	v_and_b32_e32 v63, 0xffff0000, v63
	v_pk_mul_f32 v[62:63], v[58:59], v[62:63] op_sel:[1,0]
	v_lshlrev_b32_e32 v76, 16, v64
	v_pk_fma_f32 v[62:63], v[78:79], v[54:55], v[62:63] op_sel:[0,1,0]
	v_and_b32_e32 v77, 0xffff0000, v64
	v_lshlrev_b32_e32 v64, 16, v65
	v_and_b32_e32 v65, 0xffff0000, v65
	s_waitcnt vmcnt(59)
	v_lshlrev_b32_e32 v78, 16, v50
	v_and_b32_e32 v79, 0xffff0000, v50
	v_lshlrev_b32_e32 v50, 16, v51
	v_and_b32_e32 v51, 0xffff0000, v51
	v_pk_mul_f32 v[64:65], v[58:59], v[64:65] op_sel:[1,0]
	v_pk_mul_f32 v[50:51], v[58:59], v[50:51] op_sel:[1,0]
	v_pk_fma_f32 v[64:65], v[80:81], v[54:55], v[64:65] op_sel:[0,1,0]
	v_pk_fma_f32 v[80:81], v[96:97], v[54:55], v[50:51] op_sel:[0,1,0]
	v_lshlrev_b32_e32 v50, 16, v52
	v_and_b32_e32 v51, 0xffff0000, v52
	v_pk_mul_f32 v[74:75], v[58:59], v[74:75] op_sel:[1,0]
	v_pk_mul_f32 v[50:51], v[58:59], v[50:51] op_sel:[1,0]
	v_pk_fma_f32 v[74:75], v[90:91], v[54:55], v[74:75] op_sel:[0,1,0]
	v_pk_mul_f32 v[76:77], v[58:59], v[76:77] op_sel:[1,0]
	v_pk_fma_f32 v[90:91], v[98:99], v[54:55], v[50:51] op_sel:[0,1,0]
	v_lshlrev_b32_e32 v50, 16, v53
	v_and_b32_e32 v51, 0xffff0000, v53
	v_pk_fma_f32 v[76:77], v[92:93], v[54:55], v[76:77] op_sel:[0,1,0]
	v_pk_mul_f32 v[78:79], v[58:59], v[78:79] op_sel:[1,0]
	v_pk_mul_f32 v[50:51], v[58:59], v[50:51] op_sel:[1,0]
	v_add_co_u32_e32 v58, vcc, s7, v86
	v_pk_fma_f32 v[78:79], v[94:95], v[54:55], v[78:79] op_sel:[0,1,0]
	v_pk_fma_f32 v[54:55], v[100:101], v[54:55], v[50:51] op_sel:[0,1,0]
	v_cvt_pk_bf16_f32 v50, v74, v75
	v_cvt_pk_bf16_f32 v51, v62, v63
	v_cvt_pk_bf16_f32 v52, v76, v77
	v_cvt_pk_bf16_f32 v53, v64, v65
	v_addc_co_u32_e32 v59, vcc, 0, v87, vcc
	global_store_dwordx4 v[58:59], v[50:53], off
	s_mov_b32 s7, 0x27be0000
	v_readlane_b32 s44, v245, 33
	v_cvt_pk_bf16_f32 v50, v78, v79
	v_cvt_pk_bf16_f32 v51, v80, v81
	v_cvt_pk_bf16_f32 v52, v90, v91
	v_cvt_pk_bf16_f32 v53, v54, v55
	global_store_dwordx4 v[58:59], v[50:53], off offset:512
	s_waitcnt vmcnt(59)
	v_lshlrev_b32_e32 v58, 16, v42
	v_and_b32_e32 v59, 0xffff0000, v42
	v_lshlrev_b32_e32 v50, 16, v46
	v_and_b32_e32 v51, 0xffff0000, v46
	v_lshlrev_b32_e32 v46, 16, v47
	v_and_b32_e32 v47, 0xffff0000, v47
	v_lshlrev_b32_e32 v42, 16, v43
	v_and_b32_e32 v43, 0xffff0000, v43
	v_pk_mul_f32 v[46:47], v[60:61], v[46:47] op_sel_hi:[0,1]
	v_pk_mul_f32 v[42:43], v[60:61], v[42:43] op_sel_hi:[0,1]
	v_pk_fma_f32 v[46:47], v[62:63], v[56:57], v[46:47] op_sel_hi:[1,0,1]
	v_lshlrev_b32_e32 v52, 16, v48
	v_and_b32_e32 v53, 0xffff0000, v48
	v_lshlrev_b32_e32 v48, 16, v49
	v_and_b32_e32 v49, 0xffff0000, v49
	v_pk_fma_f32 v[62:63], v[80:81], v[56:57], v[42:43] op_sel_hi:[1,0,1]
	v_lshlrev_b32_e32 v42, 16, v44
	v_and_b32_e32 v43, 0xffff0000, v44
	v_pk_mul_f32 v[48:49], v[60:61], v[48:49] op_sel_hi:[0,1]
	v_pk_mul_f32 v[42:43], v[60:61], v[42:43] op_sel_hi:[0,1]
	v_pk_mul_f32 v[50:51], v[60:61], v[50:51] op_sel_hi:[0,1]
	v_pk_mul_f32 v[52:53], v[60:61], v[52:53] op_sel_hi:[0,1]
	v_pk_fma_f32 v[48:49], v[64:65], v[56:57], v[48:49] op_sel_hi:[1,0,1]
	v_pk_fma_f32 v[64:65], v[90:91], v[56:57], v[42:43] op_sel_hi:[1,0,1]
	v_lshlrev_b32_e32 v42, 16, v45
	v_and_b32_e32 v43, 0xffff0000, v45
	v_pk_fma_f32 v[50:51], v[74:75], v[56:57], v[50:51] op_sel_hi:[1,0,1]
	v_pk_fma_f32 v[52:53], v[76:77], v[56:57], v[52:53] op_sel_hi:[1,0,1]
	v_pk_mul_f32 v[58:59], v[60:61], v[58:59] op_sel_hi:[0,1]
	v_pk_mul_f32 v[42:43], v[60:61], v[42:43] op_sel_hi:[0,1]
	v_add_co_u32_e32 v74, vcc, s7, v86
	v_pk_fma_f32 v[58:59], v[78:79], v[56:57], v[58:59] op_sel_hi:[1,0,1]
	v_pk_fma_f32 v[54:55], v[54:55], v[56:57], v[42:43] op_sel_hi:[1,0,1]
	v_cvt_pk_bf16_f32 v42, v50, v51
	v_cvt_pk_bf16_f32 v43, v46, v47
	v_cvt_pk_bf16_f32 v44, v52, v53
	v_cvt_pk_bf16_f32 v45, v48, v49
	v_addc_co_u32_e32 v75, vcc, 0, v87, vcc
	global_store_dwordx4 v[74:75], v[42:45], off
	s_mov_b32 s7, 0x27c00000
	v_readlane_b32 s45, v245, 34
	v_cvt_pk_bf16_f32 v42, v58, v59
	v_cvt_pk_bf16_f32 v43, v62, v63
	v_cvt_pk_bf16_f32 v44, v64, v65
	v_cvt_pk_bf16_f32 v45, v54, v55
	global_store_dwordx4 v[74:75], v[42:45], off offset:512
	v_readlane_b32 s46, v245, 35
	v_readlane_b32 s47, v245, 36
	s_waitcnt vmcnt(60)
	v_lshlrev_b32_e32 v44, 16, v38
	v_and_b32_e32 v45, 0xffff0000, v38
	v_mov_b32_e32 v38, v61
	v_mov_b32_e32 v42, v57
	v_pk_mul_f32 v[44:45], v[38:39], v[44:45] op_sel_hi:[0,1]
	v_pk_fma_f32 v[44:45], v[50:51], v[42:43], v[44:45] op_sel_hi:[1,0,1]
	v_lshlrev_b32_e32 v50, 16, v39
	v_and_b32_e32 v51, 0xffff0000, v39
	v_pk_mul_f32 v[50:51], v[38:39], v[50:51] op_sel_hi:[0,1]
	v_pk_fma_f32 v[46:47], v[46:47], v[42:43], v[50:51] op_sel_hi:[1,0,1]
	v_lshlrev_b32_e32 v50, 16, v40
	v_and_b32_e32 v51, 0xffff0000, v40
	v_lshlrev_b32_e32 v40, 16, v41
	v_and_b32_e32 v41, 0xffff0000, v41
	v_pk_mul_f32 v[40:41], v[38:39], v[40:41] op_sel_hi:[0,1]
	v_pk_fma_f32 v[40:41], v[48:49], v[42:43], v[40:41] op_sel_hi:[1,0,1]
	s_waitcnt vmcnt(59)
	v_lshlrev_b32_e32 v48, 16, v34
	v_and_b32_e32 v49, 0xffff0000, v34
	v_lshlrev_b32_e32 v34, 16, v35
	v_and_b32_e32 v35, 0xffff0000, v35
	v_pk_mul_f32 v[50:51], v[38:39], v[50:51] op_sel_hi:[0,1]
	v_pk_mul_f32 v[34:35], v[38:39], v[34:35] op_sel_hi:[0,1]
	v_pk_fma_f32 v[50:51], v[52:53], v[42:43], v[50:51] op_sel_hi:[1,0,1]
	v_pk_fma_f32 v[52:53], v[62:63], v[42:43], v[34:35] op_sel_hi:[1,0,1]
	v_lshlrev_b32_e32 v34, 16, v36
	v_and_b32_e32 v35, 0xffff0000, v36
	v_pk_mul_f32 v[34:35], v[38:39], v[34:35] op_sel_hi:[0,1]
	v_pk_fma_f32 v[56:57], v[64:65], v[42:43], v[34:35] op_sel_hi:[1,0,1]
	v_lshlrev_b32_e32 v34, 16, v37
	v_and_b32_e32 v35, 0xffff0000, v37
	v_pk_mul_f32 v[48:49], v[38:39], v[48:49] op_sel_hi:[0,1]
	v_pk_mul_f32 v[34:35], v[38:39], v[34:35] op_sel_hi:[0,1]
	v_pk_fma_f32 v[48:49], v[58:59], v[42:43], v[48:49] op_sel_hi:[1,0,1]
	v_pk_fma_f32 v[38:39], v[54:55], v[42:43], v[34:35] op_sel_hi:[1,0,1]
	v_add_co_u32_e32 v42, vcc, s7, v86
	v_cvt_pk_bf16_f32 v34, v44, v45
	v_cvt_pk_bf16_f32 v35, v46, v47
	v_cvt_pk_bf16_f32 v36, v50, v51
	v_cvt_pk_bf16_f32 v37, v40, v41
	v_addc_co_u32_e32 v43, vcc, 0, v87, vcc
	global_store_dwordx4 v[42:43], v[34:37], off
	s_mov_b32 s7, 0x27c20000
	v_readlane_b32 s48, v245, 37
	v_cvt_pk_bf16_f32 v34, v48, v49
	v_cvt_pk_bf16_f32 v35, v52, v53
	v_cvt_pk_bf16_f32 v36, v56, v57
	v_cvt_pk_bf16_f32 v37, v38, v39
	global_store_dwordx4 v[42:43], v[34:37], off offset:512
	v_readlane_b32 s49, v245, 38
	s_waitcnt vmcnt(60)
	v_lshlrev_b32_e32 v36, 16, v32
	v_and_b32_e32 v37, 0xffff0000, v32
	v_lshlrev_b32_e32 v32, 16, v33
	v_and_b32_e32 v33, 0xffff0000, v33
	s_waitcnt lgkmcnt(0)
	v_pk_mul_f32 v[32:33], v[70:71], v[32:33] op_sel_hi:[0,1]
	v_pk_fma_f32 v[32:33], v[40:41], v[66:67], v[32:33] op_sel_hi:[1,0,1]
	s_waitcnt vmcnt(59)
	v_lshlrev_b32_e32 v40, 16, v26
	v_and_b32_e32 v41, 0xffff0000, v26
	v_lshlrev_b32_e32 v26, 16, v27
	v_and_b32_e32 v27, 0xffff0000, v27
	v_pk_mul_f32 v[26:27], v[70:71], v[26:27] op_sel_hi:[0,1]
	v_lshlrev_b32_e32 v34, 16, v30
	v_and_b32_e32 v35, 0xffff0000, v30
	v_pk_fma_f32 v[42:43], v[52:53], v[66:67], v[26:27] op_sel_hi:[1,0,1]
	v_lshlrev_b32_e32 v26, 16, v28
	v_and_b32_e32 v27, 0xffff0000, v28
	v_pk_mul_f32 v[34:35], v[70:71], v[34:35] op_sel_hi:[0,1]
	v_lshlrev_b32_e32 v30, 16, v31
	v_and_b32_e32 v31, 0xffff0000, v31
	v_pk_mul_f32 v[26:27], v[70:71], v[26:27] op_sel_hi:[0,1]
	v_pk_fma_f32 v[34:35], v[44:45], v[66:67], v[34:35] op_sel_hi:[1,0,1]
	v_pk_mul_f32 v[30:31], v[70:71], v[30:31] op_sel_hi:[0,1]
	v_pk_mul_f32 v[36:37], v[70:71], v[36:37] op_sel_hi:[0,1]
	v_pk_fma_f32 v[44:45], v[56:57], v[66:67], v[26:27] op_sel_hi:[1,0,1]
	v_lshlrev_b32_e32 v26, 16, v29
	v_and_b32_e32 v27, 0xffff0000, v29
	v_pk_fma_f32 v[30:31], v[46:47], v[66:67], v[30:31] op_sel_hi:[1,0,1]
	v_pk_fma_f32 v[36:37], v[50:51], v[66:67], v[36:37] op_sel_hi:[1,0,1]
	v_pk_mul_f32 v[40:41], v[70:71], v[40:41] op_sel_hi:[0,1]
	v_pk_mul_f32 v[26:27], v[70:71], v[26:27] op_sel_hi:[0,1]
	v_add_co_u32_e32 v46, vcc, s7, v86
	v_pk_fma_f32 v[40:41], v[48:49], v[66:67], v[40:41] op_sel_hi:[1,0,1]
	v_pk_fma_f32 v[38:39], v[38:39], v[66:67], v[26:27] op_sel_hi:[1,0,1]
	v_cvt_pk_bf16_f32 v26, v34, v35
	v_cvt_pk_bf16_f32 v27, v30, v31
	v_cvt_pk_bf16_f32 v28, v36, v37
	v_cvt_pk_bf16_f32 v29, v32, v33
	v_addc_co_u32_e32 v47, vcc, 0, v87, vcc
	global_store_dwordx4 v[46:47], v[26:29], off
	s_mov_b32 s7, 0x27c40000
	s_nop 0
	v_cvt_pk_bf16_f32 v26, v40, v41
	v_cvt_pk_bf16_f32 v27, v42, v43
	v_cvt_pk_bf16_f32 v28, v44, v45
	v_cvt_pk_bf16_f32 v29, v38, v39
	global_store_dwordx4 v[46:47], v[26:29], off offset:512
	s_waitcnt vmcnt(60)
	s_nop 0
	v_lshlrev_b32_e32 v26, 16, v22
	v_and_b32_e32 v27, 0xffff0000, v22
	v_lshlrev_b32_e32 v22, 16, v23
	v_and_b32_e32 v23, 0xffff0000, v23
	v_pk_mul_f32 v[22:23], v[70:71], v[22:23] op_sel:[1,0]
	v_lshlrev_b32_e32 v28, 16, v24
	v_pk_fma_f32 v[22:23], v[30:31], v[66:67], v[22:23] op_sel:[0,1,0]
	v_and_b32_e32 v29, 0xffff0000, v24
	v_lshlrev_b32_e32 v24, 16, v25
	v_and_b32_e32 v25, 0xffff0000, v25
	s_waitcnt vmcnt(59)
	v_lshlrev_b32_e32 v30, 16, v18
	v_and_b32_e32 v31, 0xffff0000, v18
	v_lshlrev_b32_e32 v18, 16, v19
	v_and_b32_e32 v19, 0xffff0000, v19
	v_pk_mul_f32 v[24:25], v[70:71], v[24:25] op_sel:[1,0]
	v_pk_mul_f32 v[18:19], v[70:71], v[18:19] op_sel:[1,0]
	v_pk_fma_f32 v[24:25], v[32:33], v[66:67], v[24:25] op_sel:[0,1,0]
	v_pk_fma_f32 v[32:33], v[42:43], v[66:67], v[18:19] op_sel:[0,1,0]
	v_lshlrev_b32_e32 v18, 16, v20
	v_and_b32_e32 v19, 0xffff0000, v20
	v_pk_mul_f32 v[26:27], v[70:71], v[26:27] op_sel:[1,0]
	v_pk_mul_f32 v[18:19], v[70:71], v[18:19] op_sel:[1,0]
	v_pk_fma_f32 v[26:27], v[34:35], v[66:67], v[26:27] op_sel:[0,1,0]
	v_pk_fma_f32 v[34:35], v[44:45], v[66:67], v[18:19] op_sel:[0,1,0]
	v_lshlrev_b32_e32 v18, 16, v21
	v_and_b32_e32 v19, 0xffff0000, v21
	v_pk_mul_f32 v[28:29], v[70:71], v[28:29] op_sel:[1,0]
	v_pk_mul_f32 v[18:19], v[70:71], v[18:19] op_sel:[1,0]
	v_pk_fma_f32 v[28:29], v[36:37], v[66:67], v[28:29] op_sel:[0,1,0]
	v_pk_mul_f32 v[30:31], v[70:71], v[30:31] op_sel:[1,0]
	v_pk_fma_f32 v[36:37], v[38:39], v[66:67], v[18:19] op_sel:[0,1,0]
	v_add_co_u32_e32 v38, vcc, s7, v86
	v_pk_fma_f32 v[30:31], v[40:41], v[66:67], v[30:31] op_sel:[0,1,0]
	v_cvt_pk_bf16_f32 v18, v26, v27
	v_cvt_pk_bf16_f32 v19, v22, v23
	v_cvt_pk_bf16_f32 v20, v28, v29
	v_cvt_pk_bf16_f32 v21, v24, v25
	v_addc_co_u32_e32 v39, vcc, 0, v87, vcc
	global_store_dwordx4 v[38:39], v[18:21], off
	s_mov_b32 s7, 0x27c60000
	s_nop 0
	v_cvt_pk_bf16_f32 v18, v30, v31
	v_cvt_pk_bf16_f32 v19, v32, v33
	v_cvt_pk_bf16_f32 v20, v34, v35
	v_cvt_pk_bf16_f32 v21, v36, v37
	global_store_dwordx4 v[38:39], v[18:21], off offset:512
	s_waitcnt vmcnt(60)
	s_nop 0
	v_lshlrev_b32_e32 v18, 16, v14
	v_and_b32_e32 v19, 0xffff0000, v14
	v_lshlrev_b32_e32 v14, 16, v15
	v_and_b32_e32 v15, 0xffff0000, v15
	v_pk_mul_f32 v[14:15], v[72:73], v[14:15] op_sel_hi:[0,1]
	v_pk_fma_f32 v[14:15], v[22:23], v[68:69], v[14:15] op_sel_hi:[1,0,1]
	v_lshlrev_b32_e32 v20, 16, v16
	v_and_b32_e32 v21, 0xffff0000, v16
	v_lshlrev_b32_e32 v16, 16, v17
	v_and_b32_e32 v17, 0xffff0000, v17
	s_waitcnt vmcnt(59)
	v_lshlrev_b32_e32 v22, 16, v10
	v_and_b32_e32 v23, 0xffff0000, v10
	v_lshlrev_b32_e32 v10, 16, v11
	v_and_b32_e32 v11, 0xffff0000, v11
	v_pk_mul_f32 v[16:17], v[72:73], v[16:17] op_sel_hi:[0,1]
	v_pk_mul_f32 v[10:11], v[72:73], v[10:11] op_sel_hi:[0,1]
	v_pk_fma_f32 v[16:17], v[24:25], v[68:69], v[16:17] op_sel_hi:[1,0,1]
	v_pk_fma_f32 v[24:25], v[32:33], v[68:69], v[10:11] op_sel_hi:[1,0,1]
	v_lshlrev_b32_e32 v10, 16, v12
	v_and_b32_e32 v11, 0xffff0000, v12
	v_pk_mul_f32 v[18:19], v[72:73], v[18:19] op_sel_hi:[0,1]
	v_pk_mul_f32 v[10:11], v[72:73], v[10:11] op_sel_hi:[0,1]
	v_pk_fma_f32 v[18:19], v[26:27], v[68:69], v[18:19] op_sel_hi:[1,0,1]
	v_pk_mul_f32 v[20:21], v[72:73], v[20:21] op_sel_hi:[0,1]
	v_pk_mul_f32 v[22:23], v[72:73], v[22:23] op_sel_hi:[0,1]
	v_pk_fma_f32 v[26:27], v[34:35], v[68:69], v[10:11] op_sel_hi:[1,0,1]
	v_lshlrev_b32_e32 v10, 16, v13
	v_and_b32_e32 v11, 0xffff0000, v13
	v_pk_fma_f32 v[20:21], v[28:29], v[68:69], v[20:21] op_sel_hi:[1,0,1]
	v_pk_fma_f32 v[22:23], v[30:31], v[68:69], v[22:23] op_sel_hi:[1,0,1]
	v_pk_mul_f32 v[10:11], v[72:73], v[10:11] op_sel_hi:[0,1]
	v_add_co_u32_e32 v30, vcc, s7, v86
	v_pk_fma_f32 v[28:29], v[36:37], v[68:69], v[10:11] op_sel_hi:[1,0,1]
	v_cvt_pk_bf16_f32 v10, v18, v19
	v_cvt_pk_bf16_f32 v11, v14, v15
	v_cvt_pk_bf16_f32 v12, v20, v21
	v_cvt_pk_bf16_f32 v13, v16, v17
	v_addc_co_u32_e32 v31, vcc, 0, v87, vcc
	global_store_dwordx4 v[30:31], v[10:13], off
	s_mov_b32 s7, 0x27c80000
	s_nop 0
	v_cvt_pk_bf16_f32 v10, v22, v23
	v_cvt_pk_bf16_f32 v11, v24, v25
	v_cvt_pk_bf16_f32 v12, v26, v27
	v_cvt_pk_bf16_f32 v13, v28, v29
	global_store_dwordx4 v[30:31], v[10:13], off offset:512
	s_waitcnt vmcnt(60)
	s_nop 0
	v_lshlrev_b32_e32 v12, 16, v6
	v_and_b32_e32 v13, 0xffff0000, v6
	v_mov_b32_e32 v6, v73
	v_mov_b32_e32 v10, v69
	v_pk_mul_f32 v[12:13], v[6:7], v[12:13] op_sel_hi:[0,1]
	v_pk_fma_f32 v[90:91], v[18:19], v[10:11], v[12:13] op_sel_hi:[1,0,1]
	v_lshlrev_b32_e32 v12, 16, v7
	v_and_b32_e32 v13, 0xffff0000, v7
	v_pk_mul_f32 v[12:13], v[6:7], v[12:13] op_sel_hi:[0,1]
	v_pk_fma_f32 v[92:93], v[14:15], v[10:11], v[12:13] op_sel_hi:[1,0,1]
	v_lshlrev_b32_e32 v12, 16, v8
	v_and_b32_e32 v13, 0xffff0000, v8
	v_lshlrev_b32_e32 v8, 16, v9
	v_and_b32_e32 v9, 0xffff0000, v9
	v_pk_mul_f32 v[8:9], v[6:7], v[8:9] op_sel_hi:[0,1]
	v_pk_fma_f32 v[96:97], v[16:17], v[10:11], v[8:9] op_sel_hi:[1,0,1]
	s_waitcnt vmcnt(59)
	v_lshlrev_b32_e32 v8, 16, v2
	v_and_b32_e32 v9, 0xffff0000, v2
	v_lshlrev_b32_e32 v2, 16, v3
	v_and_b32_e32 v3, 0xffff0000, v3
	v_pk_mul_f32 v[2:3], v[6:7], v[2:3] op_sel_hi:[0,1]
	v_pk_fma_f32 v[100:101], v[24:25], v[10:11], v[2:3] op_sel_hi:[1,0,1]
	v_lshlrev_b32_e32 v2, 16, v4
	v_and_b32_e32 v3, 0xffff0000, v4
	v_pk_mul_f32 v[2:3], v[6:7], v[2:3] op_sel_hi:[0,1]
	v_pk_mul_f32 v[12:13], v[6:7], v[12:13] op_sel_hi:[0,1]
	v_pk_fma_f32 v[102:103], v[26:27], v[10:11], v[2:3] op_sel_hi:[1,0,1]
	v_lshlrev_b32_e32 v2, 16, v5
	v_and_b32_e32 v3, 0xffff0000, v5
	v_pk_fma_f32 v[94:95], v[20:21], v[10:11], v[12:13] op_sel_hi:[1,0,1]
	v_pk_mul_f32 v[8:9], v[6:7], v[8:9] op_sel_hi:[0,1]
	v_pk_mul_f32 v[2:3], v[6:7], v[2:3] op_sel_hi:[0,1]
	v_add_co_u32_e32 v6, vcc, s7, v86
	v_pk_fma_f32 v[98:99], v[22:23], v[10:11], v[8:9] op_sel_hi:[1,0,1]
	v_pk_fma_f32 v[104:105], v[28:29], v[10:11], v[2:3] op_sel_hi:[1,0,1]
	v_cvt_pk_bf16_f32 v2, v90, v91
	v_cvt_pk_bf16_f32 v3, v92, v93
	v_cvt_pk_bf16_f32 v4, v94, v95
	v_cvt_pk_bf16_f32 v5, v96, v97
	v_addc_co_u32_e32 v7, vcc, 0, v87, vcc
	global_store_dwordx4 v[6:7], v[2:5], off
	s_mov_b32 s7, 0x23c80000
	s_nop 0
	v_cvt_pk_bf16_f32 v2, v98, v99
	v_cvt_pk_bf16_f32 v3, v100, v101
	v_cvt_pk_bf16_f32 v4, v102, v103
	v_cvt_pk_bf16_f32 v5, v104, v105
	global_store_dwordx4 v[6:7], v[2:5], off offset:512
	s_nop 1
	v_add_co_u32_e32 v2, vcc, s7, v88
	s_mov_b32 s7, 0
	s_nop 0
	v_addc_co_u32_e32 v3, vcc, 0, v89, vcc
	s_waitcnt vmcnt(16)
	v_mov_b32_e32 v78, v110
	v_mov_b32_e32 v79, v111
	v_mov_b32_e32 v80, v112
	v_mov_b32_e32 v81, v113
	v_lshl_add_u64 v[2:3], v[88:89], 0, s[8:9]
	v_mov_b32_e32 v74, v114
	v_mov_b32_e32 v75, v115
	v_mov_b32_e32 v76, v116
	v_mov_b32_e32 v77, v117
	s_mov_b64 s[8:9], 0x23ca0000
	v_lshl_add_u64 v[2:3], v[88:89], 0, s[8:9]
	s_mov_b32 s8, 0x23ca0000
	v_add_co_u32_e32 v4, vcc, s8, v88
	s_mov_b64 s[8:9], 0x23cc0000
	s_nop 0
	v_addc_co_u32_e32 v5, vcc, 0, v89, vcc
	v_mov_b32_e32 v70, v118
	v_mov_b32_e32 v71, v119
	v_mov_b32_e32 v72, v120
	v_mov_b32_e32 v73, v121
	v_mov_b32_e32 v58, v122
	v_mov_b32_e32 v59, v123
	v_mov_b32_e32 v60, v124
	v_mov_b32_e32 v61, v125
	v_lshl_add_u64 v[2:3], v[88:89], 0, s[8:9]
	s_mov_b32 s8, 0x23cc0000
	v_add_co_u32_e32 v4, vcc, s8, v88
	s_mov_b64 s[8:9], 0x23ce0000
	s_nop 0
	v_addc_co_u32_e32 v5, vcc, 0, v89, vcc
	v_mov_b32_e32 v54, v126
	v_mov_b32_e32 v55, v127
	v_mov_b32_e32 v56, v128
	v_mov_b32_e32 v57, v129
	v_mov_b32_e32 v42, v130
	v_mov_b32_e32 v43, v131
	v_mov_b32_e32 v44, v132
	v_mov_b32_e32 v45, v133
	v_lshl_add_u64 v[2:3], v[88:89], 0, s[8:9]
	s_mov_b32 s8, 0x23ce0000
	v_add_co_u32_e32 v4, vcc, s8, v88
	s_mov_b64 s[8:9], 0x23d00000
	s_nop 0
	v_addc_co_u32_e32 v5, vcc, 0, v89, vcc
	v_mov_b32_e32 v38, v134
	v_mov_b32_e32 v39, v135
	v_mov_b32_e32 v40, v136
	v_mov_b32_e32 v41, v137
	v_mov_b32_e32 v34, v138
	v_mov_b32_e32 v35, v139
	v_mov_b32_e32 v36, v140
	v_mov_b32_e32 v37, v141
	v_lshl_add_u64 v[2:3], v[88:89], 0, s[8:9]
	s_mov_b32 s8, 0x23d00000
	v_add_co_u32_e32 v4, vcc, s8, v88
	s_mov_b64 s[8:9], 0x23d20000
	s_nop 0
	v_addc_co_u32_e32 v5, vcc, 0, v89, vcc
	v_mov_b32_e32 v30, v142
	v_mov_b32_e32 v31, v143
	v_mov_b32_e32 v32, v144
	v_mov_b32_e32 v33, v145
	v_mov_b32_e32 v26, v146
	v_mov_b32_e32 v27, v147
	v_mov_b32_e32 v28, v148
	v_mov_b32_e32 v29, v149
	v_lshl_add_u64 v[2:3], v[88:89], 0, s[8:9]
	s_mov_b32 s8, 0x23d20000
	v_add_co_u32_e32 v4, vcc, s8, v88
	s_mov_b64 s[8:9], 0x23d40000
	s_nop 0
	v_addc_co_u32_e32 v5, vcc, 0, v89, vcc
	v_mov_b32_e32 v22, v150
	v_mov_b32_e32 v23, v151
	v_mov_b32_e32 v24, v152
	v_mov_b32_e32 v25, v153
	v_mov_b32_e32 v18, v154
	v_mov_b32_e32 v19, v155
	v_mov_b32_e32 v20, v156
	v_mov_b32_e32 v21, v157
	v_lshl_add_u64 v[2:3], v[88:89], 0, s[8:9]
	s_mov_b32 s8, 0x23d40000
	v_add_co_u32_e32 v4, vcc, s8, v88
	s_mov_b64 s[8:9], 0x23d60000
	s_nop 0
	v_addc_co_u32_e32 v5, vcc, 0, v89, vcc
	v_mov_b32_e32 v14, v158
	v_mov_b32_e32 v15, v159
	v_mov_b32_e32 v16, v160
	v_mov_b32_e32 v17, v161
	v_mov_b32_e32 v10, v162
	v_mov_b32_e32 v11, v163
	v_mov_b32_e32 v12, v164
	v_mov_b32_e32 v13, v165
	v_lshl_add_u64 v[46:47], v[88:89], 0, s[8:9]
	s_mov_b32 s8, 0x23d60000
	v_add_co_u32_e32 v48, vcc, s8, v88
	s_mov_b32 s8, 0x27ca0000
	s_nop 0
	v_addc_co_u32_e32 v49, vcc, 0, v89, vcc
	v_mov_b32_e32 v6, v166
	v_mov_b32_e32 v7, v167
	v_mov_b32_e32 v8, v168
	v_mov_b32_e32 v9, v169
	v_mov_b32_e32 v2, v170
	v_mov_b32_e32 v3, v171
	v_mov_b32_e32 v4, v172
	v_mov_b32_e32 v5, v173
	v_cmp_gt_i32_e32 vcc, 0x100, v84
	s_and_b64 s[12:13], s[2:3], vcc
	s_and_saveexec_b64 s[14:15], s[12:13]
	s_cbranch_execz .Lmy_p3_nonrm
	s_lshl_b64 s[12:13], s[4:5], 2
	s_add_u32 s12, s12, s96
	s_addc_u32 s13, s13, s97
	v_mov_b32_e32 v130, v84
	v_ashrrev_i32_e32 v131, 31, v84
	v_lshlrev_b64 v[130:131], 2, v[130:131]
	v_lshl_add_u64 v[130:131], s[12:13], 0, v[130:131]
	s_mov_b64 s[12:13], 0x2bb80000
	v_lshl_add_u64 v[132:133], v[130:131], 0, s[12:13]
	global_load_dword v114, v[132:133], off
	global_load_dword v115, v[132:133], off offset:1024
	global_load_dword v116, v[132:133], off offset:2048
	global_load_dword v117, v[132:133], off offset:3072
	s_mov_b64 s[12:13], 0x2bb81000
	v_lshl_add_u64 v[132:133], v[130:131], 0, s[12:13]
	global_load_dword v118, v[132:133], off
	global_load_dword v119, v[132:133], off offset:1024
	global_load_dword v120, v[132:133], off offset:2048
	global_load_dword v121, v[132:133], off offset:3072
	s_mov_b64 s[12:13], 0x2bb82000
	v_lshl_add_u64 v[132:133], v[130:131], 0, s[12:13]
	global_load_dword v122, v[132:133], off
	global_load_dword v123, v[132:133], off offset:1024
	global_load_dword v124, v[132:133], off offset:2048
	global_load_dword v125, v[132:133], off offset:3072
	s_mov_b64 s[12:13], 0x2bb83000
	v_lshl_add_u64 v[132:133], v[130:131], 0, s[12:13]
	global_load_dword v126, v[132:133], off
	global_load_dword v127, v[132:133], off offset:1024
	global_load_dword v128, v[132:133], off offset:2048
	global_load_dword v129, v[132:133], off offset:3072
.Lmy_p3_nonrm:
	s_or_b64 exec, exec, s[14:15]
	ds_read_b128 v[62:65], v83 offset:96
	ds_read_b128 v[66:69], v83 offset:32
	ds_read_b128 v[50:53], v83 offset:112
	v_lshlrev_b32_e32 v46, 16, v78
	v_and_b32_e32 v47, 0xffff0000, v78
	v_lshlrev_b32_e32 v78, 16, v79
	v_and_b32_e32 v79, 0xffff0000, v79
	s_waitcnt lgkmcnt(2)
	v_pk_mul_f32 v[88:89], v[62:63], v[46:47] op_sel_hi:[0,1]
	v_pk_mul_f32 v[78:79], v[62:63], v[78:79] op_sel_hi:[0,1]
	s_waitcnt lgkmcnt(1)
	v_pk_fma_f32 v[88:89], v[90:91], v[66:67], v[88:89] op_sel_hi:[1,0,1]
	v_pk_fma_f32 v[78:79], v[92:93], v[66:67], v[78:79] op_sel_hi:[1,0,1]
	v_lshlrev_b32_e32 v90, 16, v80
	v_and_b32_e32 v91, 0xffff0000, v80
	v_lshlrev_b32_e32 v92, 16, v74
	v_and_b32_e32 v93, 0xffff0000, v74
	v_lshlrev_b32_e32 v74, 16, v75
	v_and_b32_e32 v75, 0xffff0000, v75
	v_pk_mul_f32 v[90:91], v[62:63], v[90:91] op_sel_hi:[0,1]
	v_pk_mul_f32 v[74:75], v[62:63], v[74:75] op_sel_hi:[0,1]
	v_pk_fma_f32 v[90:91], v[94:95], v[66:67], v[90:91] op_sel_hi:[1,0,1]
	v_lshlrev_b32_e32 v80, 16, v81
	v_and_b32_e32 v81, 0xffff0000, v81
	v_pk_fma_f32 v[94:95], v[100:101], v[66:67], v[74:75] op_sel_hi:[1,0,1]
	v_lshlrev_b32_e32 v74, 16, v76
	v_and_b32_e32 v75, 0xffff0000, v76
	v_pk_mul_f32 v[80:81], v[62:63], v[80:81] op_sel_hi:[0,1]
	v_pk_mul_f32 v[74:75], v[62:63], v[74:75] op_sel_hi:[0,1]
	v_pk_fma_f32 v[80:81], v[96:97], v[66:67], v[80:81] op_sel_hi:[1,0,1]
	v_pk_fma_f32 v[96:97], v[102:103], v[66:67], v[74:75] op_sel_hi:[1,0,1]
	v_lshlrev_b32_e32 v74, 16, v77
	v_and_b32_e32 v75, 0xffff0000, v77
	v_pk_mul_f32 v[92:93], v[62:63], v[92:93] op_sel_hi:[0,1]
	v_pk_mul_f32 v[74:75], v[62:63], v[74:75] op_sel_hi:[0,1]
	v_add_co_u32_e32 v100, vcc, s8, v86
	v_pk_fma_f32 v[92:93], v[98:99], v[66:67], v[92:93] op_sel_hi:[1,0,1]
	v_pk_fma_f32 v[98:99], v[104:105], v[66:67], v[74:75] op_sel_hi:[1,0,1]
	v_cvt_pk_bf16_f32 v74, v88, v89
	v_cvt_pk_bf16_f32 v75, v78, v79
	v_cvt_pk_bf16_f32 v76, v90, v91
	v_cvt_pk_bf16_f32 v77, v80, v81
	v_addc_co_u32_e32 v101, vcc, 0, v87, vcc
	global_store_dwordx4 v[100:101], v[74:77], off
	s_mov_b32 s8, 0x27cc0000
	ds_read_b128 v[46:49], v83 offset:48
	v_cvt_pk_bf16_f32 v74, v92, v93
	v_cvt_pk_bf16_f32 v75, v94, v95
	v_cvt_pk_bf16_f32 v76, v96, v97
	v_cvt_pk_bf16_f32 v77, v98, v99
	global_store_dwordx4 v[100:101], v[74:77], off offset:512
	s_nop 0
	v_lshlrev_b32_e32 v74, 16, v70
	v_and_b32_e32 v75, 0xffff0000, v70
	v_lshlrev_b32_e32 v70, 16, v71
	v_and_b32_e32 v71, 0xffff0000, v71
	v_pk_mul_f32 v[70:71], v[62:63], v[70:71] op_sel:[1,0]
	v_lshlrev_b32_e32 v76, 16, v72
	v_pk_fma_f32 v[70:71], v[78:79], v[66:67], v[70:71] op_sel:[0,1,0]
	v_and_b32_e32 v77, 0xffff0000, v72
	v_lshlrev_b32_e32 v72, 16, v73
	v_and_b32_e32 v73, 0xffff0000, v73
	v_lshlrev_b32_e32 v78, 16, v58
	v_and_b32_e32 v79, 0xffff0000, v58
	v_lshlrev_b32_e32 v58, 16, v59
	v_and_b32_e32 v59, 0xffff0000, v59
	v_pk_mul_f32 v[72:73], v[62:63], v[72:73] op_sel:[1,0]
	v_pk_mul_f32 v[58:59], v[62:63], v[58:59] op_sel:[1,0]
	v_pk_fma_f32 v[72:73], v[80:81], v[66:67], v[72:73] op_sel:[0,1,0]
	v_pk_fma_f32 v[80:81], v[94:95], v[66:67], v[58:59] op_sel:[0,1,0]
	v_lshlrev_b32_e32 v58, 16, v60
	v_and_b32_e32 v59, 0xffff0000, v60
	v_pk_mul_f32 v[74:75], v[62:63], v[74:75] op_sel:[1,0]
	v_pk_mul_f32 v[58:59], v[62:63], v[58:59] op_sel:[1,0]
	v_pk_fma_f32 v[74:75], v[88:89], v[66:67], v[74:75] op_sel:[0,1,0]
	v_pk_fma_f32 v[88:89], v[96:97], v[66:67], v[58:59] op_sel:[0,1,0]
	v_lshlrev_b32_e32 v58, 16, v61
	v_and_b32_e32 v59, 0xffff0000, v61
	v_pk_mul_f32 v[76:77], v[62:63], v[76:77] op_sel:[1,0]
	v_pk_mul_f32 v[78:79], v[62:63], v[78:79] op_sel:[1,0]
	v_pk_mul_f32 v[58:59], v[62:63], v[58:59] op_sel:[1,0]
	v_pk_fma_f32 v[76:77], v[90:91], v[66:67], v[76:77] op_sel:[0,1,0]
	v_pk_fma_f32 v[78:79], v[92:93], v[66:67], v[78:79] op_sel:[0,1,0]
	v_pk_fma_f32 v[62:63], v[98:99], v[66:67], v[58:59] op_sel:[0,1,0]
	v_add_co_u32_e32 v66, vcc, s8, v86
	v_cvt_pk_bf16_f32 v58, v74, v75
	v_cvt_pk_bf16_f32 v59, v70, v71
	v_cvt_pk_bf16_f32 v60, v76, v77
	v_cvt_pk_bf16_f32 v61, v72, v73
	v_addc_co_u32_e32 v67, vcc, 0, v87, vcc
	global_store_dwordx4 v[66:67], v[58:61], off
	s_mov_b32 s8, 0x27ce0000
	s_nop 0
	v_cvt_pk_bf16_f32 v58, v78, v79
	v_cvt_pk_bf16_f32 v59, v80, v81
	v_cvt_pk_bf16_f32 v60, v88, v89
	v_cvt_pk_bf16_f32 v61, v62, v63
	global_store_dwordx4 v[66:67], v[58:61], off offset:512
	v_lshlrev_b32_e32 v66, 16, v42
	v_and_b32_e32 v67, 0xffff0000, v42
	v_lshlrev_b32_e32 v58, 16, v54
	v_and_b32_e32 v59, 0xffff0000, v54
	v_lshlrev_b32_e32 v54, 16, v55
	v_and_b32_e32 v55, 0xffff0000, v55
	v_lshlrev_b32_e32 v42, 16, v43
	v_and_b32_e32 v43, 0xffff0000, v43
	v_pk_mul_f32 v[54:55], v[64:65], v[54:55] op_sel_hi:[0,1]
	v_pk_mul_f32 v[42:43], v[64:65], v[42:43] op_sel_hi:[0,1]
	v_pk_fma_f32 v[54:55], v[70:71], v[68:69], v[54:55] op_sel_hi:[1,0,1]
	v_lshlrev_b32_e32 v60, 16, v56
	v_and_b32_e32 v61, 0xffff0000, v56
	v_lshlrev_b32_e32 v56, 16, v57
	v_and_b32_e32 v57, 0xffff0000, v57
	v_pk_fma_f32 v[70:71], v[80:81], v[68:69], v[42:43] op_sel_hi:[1,0,1]
	v_lshlrev_b32_e32 v42, 16, v44
	v_and_b32_e32 v43, 0xffff0000, v44
	v_pk_mul_f32 v[56:57], v[64:65], v[56:57] op_sel_hi:[0,1]
	v_pk_mul_f32 v[42:43], v[64:65], v[42:43] op_sel_hi:[0,1]
	v_pk_mul_f32 v[58:59], v[64:65], v[58:59] op_sel_hi:[0,1]
	v_pk_mul_f32 v[60:61], v[64:65], v[60:61] op_sel_hi:[0,1]
	v_pk_fma_f32 v[56:57], v[72:73], v[68:69], v[56:57] op_sel_hi:[1,0,1]
	v_pk_fma_f32 v[72:73], v[88:89], v[68:69], v[42:43] op_sel_hi:[1,0,1]
	v_lshlrev_b32_e32 v42, 16, v45
	v_and_b32_e32 v43, 0xffff0000, v45
	v_pk_fma_f32 v[58:59], v[74:75], v[68:69], v[58:59] op_sel_hi:[1,0,1]
	v_pk_fma_f32 v[60:61], v[76:77], v[68:69], v[60:61] op_sel_hi:[1,0,1]
	v_pk_mul_f32 v[66:67], v[64:65], v[66:67] op_sel_hi:[0,1]
	v_pk_mul_f32 v[42:43], v[64:65], v[42:43] op_sel_hi:[0,1]
	v_add_co_u32_e32 v74, vcc, s8, v86
	v_pk_fma_f32 v[66:67], v[78:79], v[68:69], v[66:67] op_sel_hi:[1,0,1]
	v_pk_fma_f32 v[62:63], v[62:63], v[68:69], v[42:43] op_sel_hi:[1,0,1]
	v_cvt_pk_bf16_f32 v42, v58, v59
	v_cvt_pk_bf16_f32 v43, v54, v55
	v_cvt_pk_bf16_f32 v44, v60, v61
	v_cvt_pk_bf16_f32 v45, v56, v57
	v_addc_co_u32_e32 v75, vcc, 0, v87, vcc
	global_store_dwordx4 v[74:75], v[42:45], off
	s_mov_b32 s8, 0x27d00000
	s_nop 0
	v_cvt_pk_bf16_f32 v42, v66, v67
	v_cvt_pk_bf16_f32 v43, v70, v71
	v_cvt_pk_bf16_f32 v44, v72, v73
	v_cvt_pk_bf16_f32 v45, v62, v63
	global_store_dwordx4 v[74:75], v[42:45], off offset:512
	s_nop 0
	v_lshlrev_b32_e32 v44, 16, v38
	v_and_b32_e32 v45, 0xffff0000, v38
	v_mov_b32_e32 v38, v65
	v_mov_b32_e32 v42, v69
	v_pk_mul_f32 v[44:45], v[38:39], v[44:45] op_sel_hi:[0,1]
	v_pk_fma_f32 v[44:45], v[58:59], v[42:43], v[44:45] op_sel_hi:[1,0,1]
	v_lshlrev_b32_e32 v58, 16, v39
	v_and_b32_e32 v59, 0xffff0000, v39
	v_pk_mul_f32 v[58:59], v[38:39], v[58:59] op_sel_hi:[0,1]
	v_pk_fma_f32 v[54:55], v[54:55], v[42:43], v[58:59] op_sel_hi:[1,0,1]
	v_lshlrev_b32_e32 v58, 16, v40
	v_and_b32_e32 v59, 0xffff0000, v40
	v_lshlrev_b32_e32 v40, 16, v41
	v_and_b32_e32 v41, 0xffff0000, v41
	v_pk_mul_f32 v[40:41], v[38:39], v[40:41] op_sel_hi:[0,1]
	v_pk_fma_f32 v[40:41], v[56:57], v[42:43], v[40:41] op_sel_hi:[1,0,1]
	v_lshlrev_b32_e32 v56, 16, v34
	v_and_b32_e32 v57, 0xffff0000, v34
	v_lshlrev_b32_e32 v34, 16, v35
	v_and_b32_e32 v35, 0xffff0000, v35
	v_pk_mul_f32 v[58:59], v[38:39], v[58:59] op_sel_hi:[0,1]
	v_pk_mul_f32 v[34:35], v[38:39], v[34:35] op_sel_hi:[0,1]
	v_pk_fma_f32 v[58:59], v[60:61], v[42:43], v[58:59] op_sel_hi:[1,0,1]
	v_pk_fma_f32 v[60:61], v[70:71], v[42:43], v[34:35] op_sel_hi:[1,0,1]
	v_lshlrev_b32_e32 v34, 16, v36
	v_and_b32_e32 v35, 0xffff0000, v36
	v_pk_mul_f32 v[34:35], v[38:39], v[34:35] op_sel_hi:[0,1]
	v_pk_fma_f32 v[64:65], v[72:73], v[42:43], v[34:35] op_sel_hi:[1,0,1]
	v_lshlrev_b32_e32 v34, 16, v37
	v_and_b32_e32 v35, 0xffff0000, v37
	v_pk_mul_f32 v[56:57], v[38:39], v[56:57] op_sel_hi:[0,1]
	v_pk_mul_f32 v[34:35], v[38:39], v[34:35] op_sel_hi:[0,1]
	v_pk_fma_f32 v[56:57], v[66:67], v[42:43], v[56:57] op_sel_hi:[1,0,1]
	v_pk_fma_f32 v[38:39], v[62:63], v[42:43], v[34:35] op_sel_hi:[1,0,1]
	v_add_co_u32_e32 v42, vcc, s8, v86
	v_cvt_pk_bf16_f32 v34, v44, v45
	v_cvt_pk_bf16_f32 v35, v54, v55
	v_cvt_pk_bf16_f32 v36, v58, v59
	v_cvt_pk_bf16_f32 v37, v40, v41
	v_addc_co_u32_e32 v43, vcc, 0, v87, vcc
	global_store_dwordx4 v[42:43], v[34:37], off
	s_mov_b32 s8, 0x27d20000
	s_nop 0
	v_cvt_pk_bf16_f32 v34, v56, v57
	v_cvt_pk_bf16_f32 v35, v60, v61
	v_cvt_pk_bf16_f32 v36, v64, v65
	v_cvt_pk_bf16_f32 v37, v38, v39
	global_store_dwordx4 v[42:43], v[34:37], off offset:512
	s_nop 0
	v_lshlrev_b32_e32 v36, 16, v32
	v_and_b32_e32 v37, 0xffff0000, v32
	v_lshlrev_b32_e32 v32, 16, v33
	v_and_b32_e32 v33, 0xffff0000, v33
	s_waitcnt lgkmcnt(1)
	v_pk_mul_f32 v[32:33], v[50:51], v[32:33] op_sel_hi:[0,1]
	s_waitcnt lgkmcnt(0)
	v_pk_fma_f32 v[32:33], v[40:41], v[46:47], v[32:33] op_sel_hi:[1,0,1]
	v_lshlrev_b32_e32 v40, 16, v26
	v_and_b32_e32 v41, 0xffff0000, v26
	v_lshlrev_b32_e32 v26, 16, v27
	v_and_b32_e32 v27, 0xffff0000, v27
	v_pk_mul_f32 v[26:27], v[50:51], v[26:27] op_sel_hi:[0,1]
	v_lshlrev_b32_e32 v34, 16, v30
	v_and_b32_e32 v35, 0xffff0000, v30
	v_pk_fma_f32 v[42:43], v[60:61], v[46:47], v[26:27] op_sel_hi:[1,0,1]
	v_lshlrev_b32_e32 v26, 16, v28
	v_and_b32_e32 v27, 0xffff0000, v28
	v_pk_mul_f32 v[34:35], v[50:51], v[34:35] op_sel_hi:[0,1]
	v_lshlrev_b32_e32 v30, 16, v31
	v_and_b32_e32 v31, 0xffff0000, v31
	v_pk_mul_f32 v[26:27], v[50:51], v[26:27] op_sel_hi:[0,1]
	v_pk_fma_f32 v[34:35], v[44:45], v[46:47], v[34:35] op_sel_hi:[1,0,1]
	v_pk_mul_f32 v[30:31], v[50:51], v[30:31] op_sel_hi:[0,1]
	v_pk_mul_f32 v[36:37], v[50:51], v[36:37] op_sel_hi:[0,1]
	v_pk_fma_f32 v[44:45], v[64:65], v[46:47], v[26:27] op_sel_hi:[1,0,1]
	v_lshlrev_b32_e32 v26, 16, v29
	v_and_b32_e32 v27, 0xffff0000, v29
	v_pk_fma_f32 v[30:31], v[54:55], v[46:47], v[30:31] op_sel_hi:[1,0,1]
	v_pk_fma_f32 v[36:37], v[58:59], v[46:47], v[36:37] op_sel_hi:[1,0,1]
	v_pk_mul_f32 v[40:41], v[50:51], v[40:41] op_sel_hi:[0,1]
	v_pk_mul_f32 v[26:27], v[50:51], v[26:27] op_sel_hi:[0,1]
	v_add_co_u32_e32 v54, vcc, s8, v86
	v_pk_fma_f32 v[40:41], v[56:57], v[46:47], v[40:41] op_sel_hi:[1,0,1]
	v_pk_fma_f32 v[38:39], v[38:39], v[46:47], v[26:27] op_sel_hi:[1,0,1]
	v_cvt_pk_bf16_f32 v26, v34, v35
	v_cvt_pk_bf16_f32 v27, v30, v31
	v_cvt_pk_bf16_f32 v28, v36, v37
	v_cvt_pk_bf16_f32 v29, v32, v33
	v_addc_co_u32_e32 v55, vcc, 0, v87, vcc
	global_store_dwordx4 v[54:55], v[26:29], off
	s_mov_b32 s8, 0x27d40000
	s_nop 0
	v_cvt_pk_bf16_f32 v26, v40, v41
	v_cvt_pk_bf16_f32 v27, v42, v43
	v_cvt_pk_bf16_f32 v28, v44, v45
	v_cvt_pk_bf16_f32 v29, v38, v39
	global_store_dwordx4 v[54:55], v[26:29], off offset:512
	s_nop 0
	v_lshlrev_b32_e32 v26, 16, v22
	v_and_b32_e32 v27, 0xffff0000, v22
	v_lshlrev_b32_e32 v22, 16, v23
	v_and_b32_e32 v23, 0xffff0000, v23
	v_pk_mul_f32 v[22:23], v[50:51], v[22:23] op_sel:[1,0]
	v_lshlrev_b32_e32 v28, 16, v24
	v_pk_fma_f32 v[22:23], v[30:31], v[46:47], v[22:23] op_sel:[0,1,0]
	v_and_b32_e32 v29, 0xffff0000, v24
	v_lshlrev_b32_e32 v24, 16, v25
	v_and_b32_e32 v25, 0xffff0000, v25
	v_lshlrev_b32_e32 v30, 16, v18
	v_and_b32_e32 v31, 0xffff0000, v18
	v_lshlrev_b32_e32 v18, 16, v19
	v_and_b32_e32 v19, 0xffff0000, v19
	v_pk_mul_f32 v[24:25], v[50:51], v[24:25] op_sel:[1,0]
	v_pk_mul_f32 v[18:19], v[50:51], v[18:19] op_sel:[1,0]
	v_pk_fma_f32 v[24:25], v[32:33], v[46:47], v[24:25] op_sel:[0,1,0]
	v_pk_fma_f32 v[32:33], v[42:43], v[46:47], v[18:19] op_sel:[0,1,0]
	v_lshlrev_b32_e32 v18, 16, v20
	v_and_b32_e32 v19, 0xffff0000, v20
	v_pk_mul_f32 v[26:27], v[50:51], v[26:27] op_sel:[1,0]
	v_pk_mul_f32 v[18:19], v[50:51], v[18:19] op_sel:[1,0]
	v_pk_fma_f32 v[26:27], v[34:35], v[46:47], v[26:27] op_sel:[0,1,0]
	v_pk_fma_f32 v[34:35], v[44:45], v[46:47], v[18:19] op_sel:[0,1,0]
	v_lshlrev_b32_e32 v18, 16, v21
	v_and_b32_e32 v19, 0xffff0000, v21
	v_pk_mul_f32 v[28:29], v[50:51], v[28:29] op_sel:[1,0]
	v_pk_mul_f32 v[18:19], v[50:51], v[18:19] op_sel:[1,0]
	v_pk_fma_f32 v[28:29], v[36:37], v[46:47], v[28:29] op_sel:[0,1,0]
	v_pk_mul_f32 v[30:31], v[50:51], v[30:31] op_sel:[1,0]
	v_pk_fma_f32 v[36:37], v[38:39], v[46:47], v[18:19] op_sel:[0,1,0]
	v_add_co_u32_e32 v38, vcc, s8, v86
	v_pk_fma_f32 v[30:31], v[40:41], v[46:47], v[30:31] op_sel:[0,1,0]
	v_cvt_pk_bf16_f32 v18, v26, v27
	v_cvt_pk_bf16_f32 v19, v22, v23
	v_cvt_pk_bf16_f32 v20, v28, v29
	v_cvt_pk_bf16_f32 v21, v24, v25
	v_addc_co_u32_e32 v39, vcc, 0, v87, vcc
	global_store_dwordx4 v[38:39], v[18:21], off
	s_mov_b32 s8, 0x27d60000
	s_nop 0
	v_cvt_pk_bf16_f32 v18, v30, v31
	v_cvt_pk_bf16_f32 v19, v32, v33
	v_cvt_pk_bf16_f32 v20, v34, v35
	v_cvt_pk_bf16_f32 v21, v36, v37
	global_store_dwordx4 v[38:39], v[18:21], off offset:512
	s_nop 0
	v_lshlrev_b32_e32 v18, 16, v14
	v_and_b32_e32 v19, 0xffff0000, v14
	v_lshlrev_b32_e32 v14, 16, v15
	v_and_b32_e32 v15, 0xffff0000, v15
	v_pk_mul_f32 v[14:15], v[52:53], v[14:15] op_sel_hi:[0,1]
	v_pk_fma_f32 v[14:15], v[22:23], v[48:49], v[14:15] op_sel_hi:[1,0,1]
	v_lshlrev_b32_e32 v20, 16, v16
	v_and_b32_e32 v21, 0xffff0000, v16
	v_lshlrev_b32_e32 v16, 16, v17
	v_and_b32_e32 v17, 0xffff0000, v17
	v_lshlrev_b32_e32 v22, 16, v10
	v_and_b32_e32 v23, 0xffff0000, v10
	v_lshlrev_b32_e32 v10, 16, v11
	v_and_b32_e32 v11, 0xffff0000, v11
	v_pk_mul_f32 v[16:17], v[52:53], v[16:17] op_sel_hi:[0,1]
	v_pk_mul_f32 v[10:11], v[52:53], v[10:11] op_sel_hi:[0,1]
	v_pk_fma_f32 v[16:17], v[24:25], v[48:49], v[16:17] op_sel_hi:[1,0,1]
	v_pk_fma_f32 v[24:25], v[32:33], v[48:49], v[10:11] op_sel_hi:[1,0,1]
	v_lshlrev_b32_e32 v10, 16, v12
	v_and_b32_e32 v11, 0xffff0000, v12
	v_pk_mul_f32 v[18:19], v[52:53], v[18:19] op_sel_hi:[0,1]
	v_pk_mul_f32 v[10:11], v[52:53], v[10:11] op_sel_hi:[0,1]
	v_pk_fma_f32 v[18:19], v[26:27], v[48:49], v[18:19] op_sel_hi:[1,0,1]
	v_pk_mul_f32 v[20:21], v[52:53], v[20:21] op_sel_hi:[0,1]
	v_pk_mul_f32 v[22:23], v[52:53], v[22:23] op_sel_hi:[0,1]
	v_pk_fma_f32 v[26:27], v[34:35], v[48:49], v[10:11] op_sel_hi:[1,0,1]
	v_lshlrev_b32_e32 v10, 16, v13
	v_and_b32_e32 v11, 0xffff0000, v13
	v_pk_fma_f32 v[20:21], v[28:29], v[48:49], v[20:21] op_sel_hi:[1,0,1]
	v_pk_fma_f32 v[22:23], v[30:31], v[48:49], v[22:23] op_sel_hi:[1,0,1]
	v_pk_mul_f32 v[10:11], v[52:53], v[10:11] op_sel_hi:[0,1]
	v_add_co_u32_e32 v30, vcc, s8, v86
	v_pk_fma_f32 v[28:29], v[36:37], v[48:49], v[10:11] op_sel_hi:[1,0,1]
	v_cvt_pk_bf16_f32 v10, v18, v19
	v_cvt_pk_bf16_f32 v11, v14, v15
	v_cvt_pk_bf16_f32 v12, v20, v21
	v_cvt_pk_bf16_f32 v13, v16, v17
	v_addc_co_u32_e32 v31, vcc, 0, v87, vcc
	global_store_dwordx4 v[30:31], v[10:13], off
	s_lshl_b64 s[8:9], s[0:1], 18
	s_add_u32 s8, s50, s8
	v_cvt_pk_bf16_f32 v10, v22, v23
	v_cvt_pk_bf16_f32 v11, v24, v25
	v_cvt_pk_bf16_f32 v12, v26, v27
	v_cvt_pk_bf16_f32 v13, v28, v29
	global_store_dwordx4 v[30:31], v[10:13], off offset:512
	s_addc_u32 s9, s51, s9
	s_lshl_b32 s6, s6, 7
	v_lshlrev_b32_e32 v10, 16, v6
	v_lshlrev_b32_e32 v11, 16, v7
	v_mul_f32_e32 v10, v53, v10
	v_and_b32_e32 v6, 0xffff0000, v6
	v_mul_f32_e32 v11, v53, v11
	v_and_b32_e32 v7, 0xffff0000, v7
	v_fmac_f32_e32 v10, v18, v49
	v_mul_f32_e32 v6, v53, v6
	v_fmac_f32_e32 v11, v14, v49
	v_mul_f32_e32 v7, v53, v7
	v_lshlrev_b32_e32 v12, 16, v8
	v_and_b32_e32 v8, 0xffff0000, v8
	v_lshlrev_b32_e32 v13, 16, v9
	v_and_b32_e32 v9, 0xffff0000, v9
	v_lshlrev_b32_e32 v14, 16, v2
	v_and_b32_e32 v2, 0xffff0000, v2
	v_mul_u32_u24_e32 v18, 0x84, v85
	v_fmac_f32_e32 v6, v19, v49
	v_fmac_f32_e32 v7, v15, v49
	v_mul_f32_e32 v12, v53, v12
	v_mul_f32_e32 v8, v53, v8
	v_mul_f32_e32 v13, v53, v13
	v_mul_f32_e32 v9, v53, v9
	v_mul_f32_e32 v2, v53, v2
	v_lshlrev_b32_e32 v15, 16, v3
	v_and_b32_e32 v3, 0xffff0000, v3
	v_add3_u32 v1, 0, v1, v18
	v_fmac_f32_e32 v12, v20, v49
	v_fmac_f32_e32 v8, v21, v49
	v_fmac_f32_e32 v13, v16, v49
	v_fmac_f32_e32 v9, v17, v49
	v_mul_f32_e32 v14, v53, v14
	v_fmac_f32_e32 v2, v23, v49
	v_mul_f32_e32 v15, v53, v15
	v_mul_f32_e32 v3, v53, v3
	v_lshlrev_b32_e32 v16, 16, v4
	v_and_b32_e32 v4, 0xffff0000, v4
	v_lshlrev_b32_e32 v17, 16, v5
	v_and_b32_e32 v5, 0xffff0000, v5
	ds_write2_b32 v1, v10, v6 offset0:128 offset1:161
	ds_write2_b32 v1, v11, v7 offset0:194 offset1:227
	v_add_u32_e32 v6, 0x400, v1
	v_fmac_f32_e32 v14, v22, v49
	v_fmac_f32_e32 v15, v24, v49
	v_fmac_f32_e32 v3, v25, v49
	v_mul_f32_e32 v16, v53, v16
	v_mul_f32_e32 v4, v53, v4
	v_mul_f32_e32 v5, v53, v5
	ds_write2_b32 v6, v12, v8 offset0:4 offset1:37
	ds_write2_b32 v6, v13, v9 offset0:70 offset1:103
	ds_write2_b32 v6, v14, v2 offset0:136 offset1:169
	ds_write2_b32 v6, v15, v3 offset0:202 offset1:235
	v_ashrrev_i32_e32 v2, 1, v84
	v_fmac_f32_e32 v16, v26, v49
	v_fmac_f32_e32 v4, v27, v49
	v_mul_f32_e32 v17, v53, v17
	v_fmac_f32_e32 v5, v29, v49
	v_add_u32_e32 v1, 0x800, v1
	v_ashrrev_i32_e32 v3, 31, v2
	v_fmac_f32_e32 v17, v28, v49
	ds_write2_b32 v1, v16, v4 offset0:12 offset1:45
	ds_write2_b32 v1, v17, v5 offset0:78 offset1:111
	v_lshlrev_b64 v[4:5], 10, v[2:3]
	v_lshlrev_b32_e32 v1, 6, v84
	v_lshl_add_u64 v[4:5], s[8:9], 0, v[4:5]
	v_and_b32_e32 v82, 64, v1
	v_mul_lo_u32 v1, v2, s10
	v_lshl_add_u64 v[4:5], v[4:5], 0, s[6:7]
	v_add3_u32 v1, 0, v1, v82
	s_waitcnt lgkmcnt(0)
	s_barrier
	v_lshl_add_u64 v[18:19], v[4:5], 0, v[82:83]
	s_mov_b64 s[6:7], 0x4080000
	s_mov_b32 s1, 0x4080000
	ds_read2_b32 v[2:3], v1 offset0:128 offset1:129
	ds_read2_b32 v[4:5], v1 offset0:130 offset1:131
	ds_read2_b32 v[6:7], v1 offset0:132 offset1:133
	ds_read2_b32 v[8:9], v1 offset0:134 offset1:135
	ds_read2_b32 v[10:11], v1 offset0:136 offset1:137
	ds_read2_b32 v[12:13], v1 offset0:138 offset1:139
	ds_read2_b32 v[14:15], v1 offset0:140 offset1:141
	ds_read2_b32 v[16:17], v1 offset0:142 offset1:143
	v_lshl_add_u64 v[20:21], v[18:19], 0, s[6:7]
	v_add_co_u32_e32 v18, vcc, s1, v18
	s_movk_i32 s1, 0x100
	s_nop 0
	v_addc_co_u32_e32 v19, vcc, 0, v19, vcc
	v_cmp_gt_i32_e32 vcc, s1, v84
	s_and_b64 s[6:7], s[2:3], vcc
	s_waitcnt lgkmcnt(6)
	global_store_dwordx4 v[18:19], v[2:5], off
	s_waitcnt lgkmcnt(4)
	global_store_dwordx4 v[20:21], v[6:9], off offset:16
	s_waitcnt lgkmcnt(2)
	global_store_dwordx4 v[20:21], v[10:13], off offset:32
	s_waitcnt lgkmcnt(0)
	global_store_dwordx4 v[20:21], v[14:17], off offset:48
	s_and_saveexec_b64 s[2:3], s[6:7]
	s_cbranch_execz .LBB0_958
	s_lshl_b64 s[4:5], s[4:5], 2
	v_ashrrev_i32_e32 v85, 31, v84
	s_add_u32 s4, s96, s4
	v_lshlrev_b64 v[2:3], 2, v[84:85]
	s_addc_u32 s5, s97, s5
	v_lshl_add_u64 v[4:5], s[4:5], 0, v[2:3]
	v_add_co_u32_e32 v8, vcc, 0x2bb80000, v4
	s_mov_b64 s[4:5], 0x2bb80000
	s_nop 0
	v_addc_co_u32_e32 v9, vcc, 0, v5, vcc
	v_add_co_u32_e32 v10, vcc, 0x2bb81000, v4
	v_lshl_add_u64 v[6:7], v[4:5], 0, s[4:5]
	s_nop 0
	v_addc_co_u32_e32 v11, vcc, 0, v5, vcc
	s_waitcnt vmcnt(18)
	v_mov_b32_e32 v23, v114
	v_mov_b32_e32 v1, v115
	v_mov_b32_e32 v40, v116
	v_mov_b32_e32 v41, v118
	v_mov_b32_e32 v42, v119
	v_mov_b32_e32 v43, v120
	v_mov_b32_e32 v44, v121
	v_mov_b32_e32 v45, v117
	v_add_co_u32_e32 v24, vcc, 0x2bb82000, v4
	s_mov_b32 s1, 0x2bc01000
	s_nop 0
	v_addc_co_u32_e32 v25, vcc, 0, v5, vcc
	v_mov_b32_e32 v46, v122
	ds_read_b128 v[6:9], v83
	ds_read_b128 v[10:13], v83 offset:16
	ds_read_b128 v[14:17], v83 offset:64
	ds_read_b128 v[18:21], v83 offset:80
	v_mov_b32_e32 v47, v123
	v_mov_b32_e32 v48, v124
	v_mov_b32_e32 v49, v125
	v_add_co_u32_e32 v28, vcc, s1, v4
	s_mov_b32 s6, 0x2bc02000
	s_nop 0
	v_addc_co_u32_e32 v29, vcc, 0, v5, vcc
	v_add_co_u32_e32 v30, vcc, s6, v4
	v_mov_b32_e32 v22, v83
	s_nop 0
	v_addc_co_u32_e32 v31, vcc, 0, v5, vcc
	v_add_co_u32_e32 v34, vcc, 0x2bb83000, v4
	s_waitcnt lgkmcnt(2)
	v_mov_b32_e32 v36, v10
	v_addc_co_u32_e32 v35, vcc, 0, v5, vcc
	v_mov_b32_e32 v50, v126
	v_mov_b32_e32 v51, v127
	v_mov_b32_e32 v52, v128
	v_mov_b32_e32 v53, v129
	v_mov_b32_e32 v24, v6
	s_waitcnt lgkmcnt(1)
	v_mov_b32_e32 v25, v14
	s_mov_b64 s[4:5], 0x2bc00000
	v_lshl_add_u64 v[26:27], v[4:5], 0, s[4:5]
	v_mov_b32_e32 v32, v8
	v_mov_b32_e32 v33, v16
	s_waitcnt lgkmcnt(0)
	v_mov_b32_e32 v37, v18
	v_add_co_u32_e32 v38, vcc, 0x2bc00000, v4
	s_mov_b32 s1, 0x2bc03000
	s_nop 0
	v_addc_co_u32_e32 v39, vcc, 0, v5, vcc
	v_add_co_u32_e32 v4, vcc, s1, v4
	s_lshl_b32 s0, s0, 8
	s_nop 0
	v_addc_co_u32_e32 v5, vcc, 0, v5, vcc
	s_ashr_i32 s1, s0, 31
	s_lshl_b64 s[0:1], s[0:1], 2
	s_add_u32 s0, s50, s0
	s_addc_u32 s1, s51, s1
	v_lshl_add_u64 v[2:3], s[0:1], 0, v[2:3]
	v_add_co_u32_e32 v2, vcc, 0x4880000, v2
	global_store_dword v[38:39], v83, off
	s_nop 0
	v_addc_co_u32_e32 v3, vcc, 0, v3, vcc
	s_waitcnt vmcnt(16)
	v_mul_f32_e32 v10, v14, v23
	v_pk_fma_f32 v[22:23], v[24:25], v[22:23], v[10:11] op_sel_hi:[1,1,0]
	s_waitcnt vmcnt(15)
	v_mul_f32_e32 v6, v1, v15
	v_mov_b32_e32 v14, v7
	v_mov_b32_e32 v23, v1
	v_pk_fma_f32 v[6:7], v[22:23], v[14:15], v[6:7] op_sel_hi:[1,1,0]
	s_waitcnt vmcnt(14)
	v_mul_f32_e32 v8, v40, v16
	v_mov_b32_e32 v7, v40
	global_store_dword v[26:27], v6, off offset:2048
	v_pk_fma_f32 v[6:7], v[6:7], v[32:33], v[8:9] op_sel_hi:[1,1,0]
	v_mov_b32_e32 v16, v9
	s_waitcnt vmcnt(10)
	v_mul_f32_e32 v10, v45, v17
	v_mov_b32_e32 v7, v45
	global_store_dword v[26:27], v6, off offset:3072
	v_pk_fma_f32 v[6:7], v[6:7], v[16:17], v[10:11] op_sel_hi:[1,1,0]
	v_mul_f32_e32 v18, v41, v18
	v_mov_b32_e32 v7, v41
	global_store_dword v[30:31], v6, off offset:-4096
	v_pk_fma_f32 v[6:7], v[6:7], v[36:37], v[18:19] op_sel_hi:[1,1,0]
	v_mov_b32_e32 v18, v11
	v_mov_b32_e32 v7, v42
	v_mul_f32_e32 v8, v42, v19
	global_store_dword v[28:29], v6, off offset:1024
	v_pk_fma_f32 v[6:7], v[6:7], v[18:19], v[8:9] op_sel_hi:[1,1,0]
	v_mov_b32_e32 v8, v12
	v_mov_b32_e32 v7, v43
	v_mov_b32_e32 v9, v20
	v_mul_f32_e32 v10, v43, v20
	global_store_dword v[28:29], v6, off offset:2048
	v_pk_fma_f32 v[6:7], v[6:7], v[8:9], v[10:11] op_sel_hi:[1,1,0]
	v_mov_b32_e32 v20, v13
	v_mov_b32_e32 v7, v44
	v_mul_f32_e32 v8, v44, v21
	global_store_dword v[26:27], v22, off offset:1024
	global_store_dword v[28:29], v6, off offset:3072
	v_pk_fma_f32 v[22:23], v[6:7], v[20:21], v[8:9] op_sel_hi:[1,1,0]
	ds_read_b128 v[6:9], v83 offset:32
	ds_read_b128 v[14:17], v83 offset:48
	ds_read_b128 v[10:13], v83 offset:96
	ds_read_b128 v[18:21], v83 offset:112
	s_waitcnt vmcnt(15)
	v_mov_b32_e32 v23, v46
	s_waitcnt lgkmcnt(3)
	v_mov_b32_e32 v24, v6
	global_store_dword v[30:31], v22, off
	s_waitcnt lgkmcnt(1)
	v_mov_b32_e32 v25, v10
	v_mul_f32_e32 v6, v46, v10
	v_pk_fma_f32 v[22:23], v[22:23], v[24:25], v[6:7] op_sel_hi:[1,1,0]
	v_mov_b32_e32 v10, v7
	s_waitcnt vmcnt(15)
	v_mov_b32_e32 v23, v47
	v_mul_f32_e32 v6, v47, v11
	v_pk_fma_f32 v[6:7], v[22:23], v[10:11], v[6:7] op_sel_hi:[1,1,0]
	v_mov_b32_e32 v10, v8
	s_waitcnt vmcnt(14)
	v_mov_b32_e32 v7, v48
	v_mov_b32_e32 v11, v12
	v_mul_f32_e32 v8, v48, v12
	global_store_dword v[30:31], v6, off offset:2048
	v_pk_fma_f32 v[6:7], v[6:7], v[10:11], v[8:9] op_sel_hi:[1,1,0]
	v_mov_b32_e32 v12, v9
	s_waitcnt vmcnt(14)
	v_mov_b32_e32 v7, v49
	v_mul_f32_e32 v8, v49, v13
	global_store_dword v[30:31], v6, off offset:3072
	v_pk_fma_f32 v[6:7], v[6:7], v[12:13], v[8:9] op_sel_hi:[1,1,0]
	v_mov_b32_e32 v8, v14
	s_waitcnt vmcnt(14)
	v_mov_b32_e32 v7, v50
	s_waitcnt lgkmcnt(0)
	v_mov_b32_e32 v9, v18
	v_mul_f32_e32 v10, v50, v18
	global_store_dword v[4:5], v6, off
	v_pk_fma_f32 v[6:7], v[6:7], v[8:9], v[10:11] op_sel_hi:[1,1,0]
	v_mov_b32_e32 v18, v15
	s_waitcnt vmcnt(14)
	v_mov_b32_e32 v7, v51
	v_mul_f32_e32 v8, v51, v19
	global_store_dword v[4:5], v6, off offset:1024
	v_pk_fma_f32 v[6:7], v[6:7], v[18:19], v[8:9] op_sel_hi:[1,1,0]
	v_mov_b32_e32 v8, v16
	s_waitcnt vmcnt(14)
	v_mov_b32_e32 v7, v52
	v_mov_b32_e32 v9, v20
	v_mul_f32_e32 v10, v52, v20
	global_store_dword v[4:5], v6, off offset:2048
	v_pk_fma_f32 v[6:7], v[6:7], v[8:9], v[10:11] op_sel_hi:[1,1,0]
	v_mov_b32_e32 v20, v17
	s_waitcnt vmcnt(14)
	v_mov_b32_e32 v7, v53
	global_store_dword v[4:5], v6, off offset:3072
	v_pk_mul_f32 v[4:5], v[6:7], v[20:21]
	global_store_dword v[30:31], v22, off offset:1024
	v_add_f32_e32 v1, v4, v5
	global_store_dword v[2:3], v1, off
